# stack + older-half priority raise also applied at every attention unit dispatch (covers decode-first workgroups)
# speedup vs baseline: 1.0003x; 1.0003x over previous
.Latt_remap_mk:
	s_lshl_b32 s2, s2, 7
	s_or_b32 s1, s2, s3
	s_lshl_b32 s2, s1, 1
	s_add_i32 s3, s1, 0x100
	s_cmpk_lt_u32 s1, 0x100
	s_cselect_b32 s83, s2, s3
.Latt_remap_done:
	v_readlane_b32 s100, v255, 8
	s_cmp_lt_u32 s100, 4
	s_cbranch_scc0 .Latt_noprio
	s_setprio 1
.Latt_noprio:
	s_cmpk_gt_i32 s83, 0x1ff
	s_cselect_b64 s[12:13], -1, 0
	s_bitcmp0_b32 s83, 0
	s_cselect_b64 s[0:1], -1, 0
	s_or_b64 s[2:3], s[12:13], s[0:1]
	s_mov_b64 s[0:1], -1
	s_and_b64 vcc, exec, s[2:3]
	s_cbranch_vccnz .LBB0_913
	s_ashr_i32 s84, s83, 2
	s_add_i32 s8, s84, 0x8010
	v_mbcnt_lo_u32_b32 v3, -1, 0
	v_mbcnt_hi_u32_b32 v3, -1, v3
	s_ashr_i32 s9, s8, 31
	v_add_u32_e32 v0, s52, v3
	s_waitcnt vmcnt(3)
	v_ashrrev_i32_e32 v134, 6, v0
	s_lshl_b64 s[0:1], s[8:9], 11
	v_readfirstlane_b32 s14, v134
	s_add_u32 s2, s28, s0
	s_addc_u32 s3, s29, s1
	s_lshl_b32 s24, s14, 7
	s_ashr_i32 s25, s24, 31
	s_lshl_b64 s[0:1], s[24:25], 1
	v_and_b32_e32 v7, 31, v3
	s_add_u32 s0, s2, s0
	s_addc_u32 s1, s3, s1
	v_lshlrev_b32_e32 v1, 3, v7
	global_load_dwordx2 v[4:5], v1, s[0:1]
	s_mul_i32 s0, s14, 0x280
	s_add_i32 s0, s0, 0
	v_bfe_u32 v6, v3, 5, 1
	s_ashr_i32 s15, s14, 31
	s_add_i32 s0, s0, 0x15000
	v_lshl_add_u32 v138, v6, 1, s0
	s_lshl_b64 s[0:1], s[14:15], 9
	v_and_b32_e32 v159, 63, v3
	v_cmp_eq_u32_e64 s[4:5], 31, v7
	s_movk_i32 s2, 0xffe0
	s_waitcnt vmcnt(0)
	v_lshlrev_b32_e32 v1, 16, v4
	v_and_b32_e32 v135, 0xffff0000, v4
	v_lshlrev_b32_e32 v136, 16, v5
	v_and_b32_e32 v137, 0xffff0000, v5
	v_lshlrev_b32_e32 v4, 12, v6
	v_mov_b32_e32 v5, v2
	v_lshl_add_u64 v[4:5], v[4:5], 0, s[0:1]
	v_readlane_b32 s0, v255, 18
	v_lshl_or_b32 v4, v7, 4, v4
	v_readlane_b32 s1, v255, 19
	s_nop 1
	v_lshl_add_u64 v[132:133], s[0:1], 0, v[4:5]
	s_branch .LBB0_798
